# k54 + 14 more POST pk_mul+s_nop pairs replaced by plain f32 multiplies
# baseline (speedup 1.0000x reference)
; DI unsigned pk2(float lo, float hi) { f32x2 x = {lo, hi}; return __builtin_bit_cast(unsigned, __builtin_convertvector(x, bf16x2_t)); }
; DI float sum16(float v) { v += __shfl_xor(v, 8); v += __shfl_xor(v, 4); v += __shfl_xor(v, 2); v += __shfl_xor(v, 1); return v; }
; DI void post_unit(const Params& p, int l, int unit, LAS unsigned char* lds) {
;     ...
;       } else if (s < 12) {
;         rope2<16>(x, hl, cs64 + t * 32);
;         const int hd = ((s & 1) ? 2 : 0) + hsel;
;         const float lg = log1pf(-exp2f(-5.0f - (float)hd));
;         const float f = (s < 10) ? expf(lg * (float)(t + 1)) : expf(lg * (float)(63 - t)) * 0.125f;
;         x *= f; *(unsigned*)pp = pk2(x[0], x[1]);
;       } else {
;         const float* gn = (s < 14) ? qnc : knc;
;         const float rs = rsqrtf(sum16(x[0] * x[0] + x[1] * x[1]) * (1.0f / 32.0f) + EPS);
;         x[0] *= rs * gn[2 * hl16]; x[1] *= rs * gn[2 * hl16 + 1]; rope2<2>(x, hl16, cs8 + t * 4);
;         if (s < 14) x *= LOG2E * 0.17677669529663687f;
;         *(unsigned*)pp = pk2(x[0], x[1]);
.LBB0_196:
	s_or_b64 exec, exec, s[18:19]
	v_add_u32_e32 v58, s36, v2
	s_waitcnt lgkmcnt(1)
	v_add_u32_e32 v67, 1, v58
	v_cvt_f32_i32_e32 v67, v67
	s_mov_b64 s[2:3], 0xa000980
	s_waitcnt lgkmcnt(0)
	v_lshl_add_u64 v[22:23], v[18:19], 0, s[2:3]
	v_mul_f32_e32 v68, v31, v67
	v_mul_f32_e32 v69, 0x3fb8aa3b, v68
	v_fma_f32 v70, v68, s64, -v69
	v_rndne_f32_e32 v71, v69
	v_fmac_f32_e32 v70, 0x32a5705f, v68
	v_sub_f32_e32 v69, v69, v71
	v_add_f32_e32 v69, v69, v70
	v_exp_f32_e32 v69, v69
	v_cvt_i32_f32_e32 v70, v71
	v_cmp_ngt_f32_e32 vcc, s65, v68
	v_ldexp_f32 v69, v69, v70
	s_nop 0
	v_cndmask_b32_e32 v69, 0, v69, vcc
	v_cmp_nlt_f32_e32 vcc, s89, v68
	s_nop 1
	v_cndmask_b32_e32 v68, v177, v69, vcc
	v_pk_mul_f32 v[20:21], v[68:69], v[20:21] op_sel_hi:[0,1]
	v_cvt_pk_bf16_f32 v20, v20, v21
	global_store_dword v[22:23], v20, off
	s_waitcnt vmcnt(29)
	v_lshlrev_b32_e32 v68, 16, v66
	v_and_b32_e32 v20, 0xffff0000, v66
	ds_bpermute_b32 v66, v26, v68
	ds_bpermute_b32 v21, v26, v20
	s_waitcnt lgkmcnt(0)
	v_mul_f32_e32 v22, v84, v68
	v_mul_f32_e32 v23, v85, v20
	v_fmac_f32_e32 v22, v86, v66
	v_fmac_f32_e32 v23, v87, v21
	s_waitcnt lgkmcnt(1)
	v_mul_f32_e32 v66, v32, v67
	v_mul_f32_e32 v67, 0x3fb8aa3b, v66
	v_fma_f32 v68, v66, s64, -v67
	v_rndne_f32_e32 v69, v67
	v_fmac_f32_e32 v68, 0x32a5705f, v66
	v_sub_f32_e32 v67, v67, v69
	v_add_f32_e32 v67, v67, v68
	v_exp_f32_e32 v67, v67
	v_cvt_i32_f32_e32 v68, v69
	v_cmp_ngt_f32_e32 vcc, s65, v66
	s_mov_b64 s[2:3], 0xa000a80
	v_lshl_add_u64 v[20:21], v[18:19], 0, s[2:3]
	v_ldexp_f32 v67, v67, v68
	v_cndmask_b32_e32 v67, 0, v67, vcc
	v_cmp_nlt_f32_e32 vcc, s89, v66
	s_nop 1
	v_cndmask_b32_e32 v66, v177, v67, vcc
	v_pk_mul_f32 v[22:23], v[66:67], v[22:23] op_sel_hi:[0,1]
	v_cvt_pk_bf16_f32 v22, v22, v23
	global_store_dword v[20:21], v22, off
	s_waitcnt vmcnt(29)
	v_lshlrev_b32_e32 v66, 16, v65
	v_and_b32_e32 v22, 0xffff0000, v65
	ds_bpermute_b32 v65, v26, v66
	ds_bpermute_b32 v23, v26, v22
	s_waitcnt lgkmcnt(0)
	v_mul_f32_e32 v20, v84, v66
	v_mul_f32_e32 v21, v85, v22
	v_fmac_f32_e32 v20, v86, v65
	v_fmac_f32_e32 v21, v87, v23
	s_waitcnt lgkmcnt(1)
	v_add_u32_e32 v65, 1, v38
	v_cvt_f32_i32_e32 v65, v65
	s_mov_b64 s[2:3], 0xa000b80
	v_lshl_add_u64 v[22:23], v[18:19], 0, s[2:3]
	v_mul_f32_e32 v66, v31, v65
	v_mul_f32_e32 v67, 0x3fb8aa3b, v66
	v_fma_f32 v68, v66, s64, -v67
	v_rndne_f32_e32 v69, v67
	v_fmac_f32_e32 v68, 0x32a5705f, v66
	v_sub_f32_e32 v67, v67, v69
	v_add_f32_e32 v67, v67, v68
	v_exp_f32_e32 v67, v67
	v_cvt_i32_f32_e32 v68, v69
	v_cmp_ngt_f32_e32 vcc, s65, v66
	v_ldexp_f32 v67, v67, v68
	s_nop 0
	v_cndmask_b32_e32 v67, 0, v67, vcc
	v_cmp_nlt_f32_e32 vcc, s89, v66
	s_nop 1
	v_cndmask_b32_e32 v66, v177, v67, vcc
	v_mul_f32_e32 v66, 0x3e000000, v66
	v_pk_mul_f32 v[20:21], v[66:67], v[20:21] op_sel_hi:[0,1]
	v_cvt_pk_bf16_f32 v20, v20, v21
	global_store_dword v[22:23], v20, off
	s_waitcnt vmcnt(29)
	v_lshlrev_b32_e32 v66, 16, v64
	v_and_b32_e32 v20, 0xffff0000, v64
	ds_bpermute_b32 v64, v26, v66
	ds_bpermute_b32 v21, v26, v20
	s_waitcnt lgkmcnt(0)
	v_mul_f32_e32 v22, v84, v66
	v_mul_f32_e32 v23, v85, v20
	v_fmac_f32_e32 v22, v86, v64
	v_fmac_f32_e32 v23, v87, v21
	s_waitcnt lgkmcnt(1)
	v_mul_f32_e32 v64, v32, v65
	v_mul_f32_e32 v65, 0x3fb8aa3b, v64
	v_fma_f32 v66, v64, s64, -v65
	v_rndne_f32_e32 v67, v65
	v_fmac_f32_e32 v66, 0x32a5705f, v64
	v_sub_f32_e32 v65, v65, v67
	v_add_f32_e32 v65, v65, v66
	v_exp_f32_e32 v65, v65
	v_cvt_i32_f32_e32 v66, v67
	v_cmp_ngt_f32_e32 vcc, s65, v64
	s_mov_b64 s[2:3], 0xa000c80
	v_lshl_add_u64 v[20:21], v[18:19], 0, s[2:3]
	v_ldexp_f32 v65, v65, v66
	v_cndmask_b32_e32 v65, 0, v65, vcc
	v_cmp_nlt_f32_e32 vcc, s89, v64
	s_nop 1
	v_cndmask_b32_e32 v64, v177, v65, vcc
	v_mul_f32_e32 v64, 0x3e000000, v64
	v_pk_mul_f32 v[22:23], v[64:65], v[22:23] op_sel_hi:[0,1]
	v_cvt_pk_bf16_f32 v22, v22, v23
	global_store_dword v[20:21], v22, off
	s_waitcnt vmcnt(29)
	v_lshlrev_b32_e32 v20, 16, v54
	v_and_b32_e32 v21, 0xffff0000, v54
	v_mul_f32_e32 v22, v20, v20
	v_fmac_f32_e32 v22, v21, v21
	s_nop 1
	v_add_f32_dpp v22, v22, v22 row_ror:8 row_mask:0xf bank_mask:0xf
	s_nop 1
	v_add_f32_dpp v22, v22, v22 row_ror:4 row_mask:0xf bank_mask:0xf
	s_nop 1
	v_add_f32_dpp v22, v22, v22 quad_perm:[2,3,0,1] row_mask:0xf bank_mask:0xf
	s_nop 1
	v_add_f32_dpp v22, v22, v22 quad_perm:[1,0,3,2] row_mask:0xf bank_mask:0xf
	v_fmamk_f32 v22, v22, 0x3d000000, v170
	v_rsq_f32_e32 v22, v22
	s_nop 0
	v_mul_f32_e32 v23, v7, v22
	v_mul_f32_e32 v22, v6, v22
	v_mul_f32_e32 v22, v22, v20
	v_mul_f32_e32 v23, v23, v21
	ds_bpermute_b32 v20, v29, v22
	ds_bpermute_b32 v21, v29, v23
	v_add_u32_e32 v54, 0, v40
	s_waitcnt lgkmcnt(0)
	v_mul_f32_e32 v22, v88, v22
	v_mul_f32_e32 v23, v89, v23
	v_fmac_f32_e32 v22, v90, v20
	v_fmac_f32_e32 v23, v91, v21
	s_mov_b64 s[2:3], 0xa001180
	v_lshl_add_u64 v[20:21], v[18:19], 0, s[2:3]
	s_mov_b32 s2, 0x3e8293ee
	v_mul_f32_e32 v22, s2, v22
	v_mul_f32_e32 v23, s2, v23
	v_cvt_pk_bf16_f32 v22, v22, v23
	global_store_dword v[20:21], v22, off
	s_waitcnt vmcnt(29)
	v_lshlrev_b32_e32 v20, 16, v63
	v_and_b32_e32 v21, 0xffff0000, v63
	v_mul_f32_e32 v22, v20, v20
	v_fmac_f32_e32 v22, v21, v21
	s_nop 1
	v_add_f32_dpp v22, v22, v22 row_ror:8 row_mask:0xf bank_mask:0xf
	s_nop 1
	v_add_f32_dpp v22, v22, v22 row_ror:4 row_mask:0xf bank_mask:0xf
	s_nop 1
	v_add_f32_dpp v22, v22, v22 quad_perm:[2,3,0,1] row_mask:0xf bank_mask:0xf
	s_nop 1
	v_add_f32_dpp v22, v22, v22 quad_perm:[1,0,3,2] row_mask:0xf bank_mask:0xf
	v_fmamk_f32 v22, v22, 0x3d000000, v170
	v_rsq_f32_e32 v22, v22
	s_nop 0
	v_mul_f32_e32 v23, v7, v22
	v_mul_f32_e32 v22, v6, v22
	v_mul_f32_e32 v22, v22, v20
	v_mul_f32_e32 v23, v23, v21
	ds_bpermute_b32 v20, v29, v22
	ds_bpermute_b32 v21, v29, v23
	s_waitcnt lgkmcnt(0)
; #define LAS __attribute__((address_space(3)))
; DI unsigned pk2(float lo, float hi) { f32x2 x = {lo, hi}; return __builtin_bit_cast(unsigned, __builtin_convertvector(x, bf16x2_t)); }
; DI float sum16(float v) { v += __shfl_xor(v, 8); v += __shfl_xor(v, 4); v += __shfl_xor(v, 2); v += __shfl_xor(v, 1); return v; }
; DI float sum32(float v) { v += __shfl_xor(v, 16); return sum16(v); }
; DI float sum64(float v) { v += __shfl_xor(v, 32); return sum32(v); }
; DI f32x2 unpk(unsigned w) { f32x2 r = {bflo(w), bfhi(w)}; return r; }
; DI void post_unit(const Params& p, int l, int unit, LAS unsigned char* lds) {
;     ...
;     for (int s = 0; s < 16; ++s) {
;       f32x2 x = unpk(raw2[hf][s]); u16* pp = row + segcol[s] + 2 * lane;
;       if (s < 2) {
;         const float rs = rsqrtf(sum32(x[0] * x[0] + x[1] * x[1]) * (1.0f / 64.0f) + EPS);
;         x[0] *= rs * qna[2 * hl]; x[1] *= rs * qna[2 * hl + 1]; rope2<4>(x, hl, cs16 + t * 8);
;         x *= LOG2E * 0.125f; *(unsigned*)pp = pk2(x[0], x[1]);
;       } else if (s == 2) {
;         const float rs = rsqrtf(sum64(x[0] * x[0] + x[1] * x[1]) * (1.0f / 128.0f) + EPS);
;         *(LAS unsigned*)(At + t * 272 + lane * 4) = pk2(x[0] * rs, x[1] * rs);
;     ...
;       } else {
;         const float* gn = (s < 14) ? qnc : knc;
;         const float rs = rsqrtf(sum16(x[0] * x[0] + x[1] * x[1]) * (1.0f / 32.0f) + EPS);
;         x[0] *= rs * gn[2 * hl16]; x[1] *= rs * gn[2 * hl16 + 1]; rope2<2>(x, hl16, cs8 + t * 4);
;         if (s < 14) x *= LOG2E * 0.17677669529663687f;
;         *(unsigned*)pp = pk2(x[0], x[1]);
	v_mul_f32_e32 v22, v88, v22
	v_mul_f32_e32 v23, v89, v23
	v_fmac_f32_e32 v22, v90, v20
	v_fmac_f32_e32 v23, v91, v21
	s_mov_b64 s[2:3], 0xa001280
	v_lshl_add_u64 v[20:21], v[18:19], 0, s[2:3]
	s_mov_b32 s2, 0x3e8293ee
	v_mul_f32_e32 v22, s2, v22
	v_mul_f32_e32 v23, s2, v23
	v_cvt_pk_bf16_f32 v22, v22, v23
	global_store_dword v[20:21], v22, off
	s_waitcnt vmcnt(29)
	v_lshlrev_b32_e32 v20, 16, v62
	v_and_b32_e32 v21, 0xffff0000, v62
	v_mul_f32_e32 v22, v20, v20
	v_fmac_f32_e32 v22, v21, v21
	s_nop 1
	v_add_f32_dpp v22, v22, v22 row_ror:8 row_mask:0xf bank_mask:0xf
	s_nop 1
	v_add_f32_dpp v22, v22, v22 row_ror:4 row_mask:0xf bank_mask:0xf
	s_nop 1
	v_add_f32_dpp v22, v22, v22 quad_perm:[2,3,0,1] row_mask:0xf bank_mask:0xf
	s_nop 1
	v_add_f32_dpp v22, v22, v22 quad_perm:[1,0,3,2] row_mask:0xf bank_mask:0xf
	v_fmamk_f32 v22, v22, 0x3d000000, v170
	v_rsq_f32_e32 v22, v22
	s_nop 0
	v_mul_f32_e32 v23, v9, v22
	v_mul_f32_e32 v22, v8, v22
	v_mul_f32_e32 v22, v22, v20
	v_mul_f32_e32 v23, v23, v21
	ds_bpermute_b32 v20, v29, v22
	ds_bpermute_b32 v21, v29, v23
	s_waitcnt lgkmcnt(0)
	v_mul_f32_e32 v22, v88, v22
	v_mul_f32_e32 v23, v89, v23
	v_fmac_f32_e32 v22, v90, v20
	v_fmac_f32_e32 v23, v91, v21
	s_mov_b64 s[2:3], 0xa001380
	v_lshl_add_u64 v[20:21], v[18:19], 0, s[2:3]
	v_cvt_pk_bf16_f32 v22, v22, v23
	global_store_dword v[20:21], v22, off
	s_waitcnt vmcnt(29)
	v_lshlrev_b32_e32 v20, 16, v61
	v_and_b32_e32 v21, 0xffff0000, v61
	v_mul_f32_e32 v22, v20, v20
	v_fmac_f32_e32 v22, v21, v21
	s_nop 1
	v_add_f32_dpp v22, v22, v22 row_ror:8 row_mask:0xf bank_mask:0xf
	s_nop 1
	v_add_f32_dpp v22, v22, v22 row_ror:4 row_mask:0xf bank_mask:0xf
	s_nop 1
	v_add_f32_dpp v22, v22, v22 quad_perm:[2,3,0,1] row_mask:0xf bank_mask:0xf
	s_nop 1
	v_add_f32_dpp v22, v22, v22 quad_perm:[1,0,3,2] row_mask:0xf bank_mask:0xf
	v_fmamk_f32 v22, v22, 0x3d000000, v170
	v_rsq_f32_e32 v22, v22
	s_nop 0
	v_mul_f32_e32 v23, v9, v22
	v_mul_f32_e32 v22, v8, v22
	v_mul_f32_e32 v22, v22, v20
	v_mul_f32_e32 v23, v23, v21
	ds_bpermute_b32 v20, v29, v22
	ds_bpermute_b32 v21, v29, v23
	s_waitcnt lgkmcnt(0)
	v_mul_f32_e32 v22, v88, v22
	v_mul_f32_e32 v23, v89, v23
	v_fmac_f32_e32 v22, v90, v20
	v_fmac_f32_e32 v23, v91, v21
	s_mov_b64 s[2:3], 0xa001480
	v_lshl_add_u64 v[18:19], v[18:19], 0, s[2:3]
	s_waitcnt lgkmcnt(1)
	v_cvt_pk_bf16_f32 v20, v22, v23
	global_store_dword v[18:19], v20, off
	s_waitcnt vmcnt(29)
	v_and_b32_e32 v19, 0xffff0000, v60
	v_lshlrev_b32_e32 v18, 16, v60
	v_mul_f32_e32 v20, v18, v18
	v_fmac_f32_e32 v20, v19, v19
	v_mov_b32_e32 v21, v20
	s_nop 1
	v_permlane16_swap_b32_e32 v20, v21
	v_add_f32_e32 v20, v20, v21
	s_nop 1
	v_add_f32_dpp v20, v20, v20 row_ror:8 row_mask:0xf bank_mask:0xf
	s_nop 1
	v_add_f32_dpp v20, v20, v20 row_ror:4 row_mask:0xf bank_mask:0xf
	s_nop 1
	v_add_f32_dpp v20, v20, v20 quad_perm:[2,3,0,1] row_mask:0xf bank_mask:0xf
	s_nop 1
	v_add_f32_dpp v20, v20, v20 quad_perm:[1,0,3,2] row_mask:0xf bank_mask:0xf
	v_fmamk_f32 v20, v20, 0x3c800000, v170
	v_rsq_f32_e32 v20, v20
	s_nop 0
	v_mul_f32_e32 v21, v5, v20
	v_mul_f32_e32 v20, v4, v20
	v_mul_f32_e32 v20, v20, v18
	v_mul_f32_e32 v21, v21, v19
	ds_bpermute_b32 v18, v28, v20
	ds_bpermute_b32 v19, v28, v21
	s_waitcnt lgkmcnt(0)
	v_mul_f32_e32 v20, v92, v20
	v_mul_f32_e32 v21, v93, v21
	v_fmac_f32_e32 v20, v94, v18
	v_fmac_f32_e32 v21, v95, v19
	s_mov_b32 s2, 0x3e38aa3b
	v_lshl_add_u64 v[18:19], v[14:15], 0, v[0:1]
	v_mul_f32_e32 v20, s2, v20
	v_mul_f32_e32 v21, s2, v21
	v_cvt_pk_bf16_f32 v22, v20, v21
	v_add_co_u32_e32 v20, vcc, 0xa002000, v18
	s_nop 1
	v_addc_co_u32_e32 v21, vcc, 0, v19, vcc
	global_store_dword v[20:21], v22, off offset:512
	s_waitcnt vmcnt(29)
	v_and_b32_e32 v21, 0xffff0000, v57
	v_lshlrev_b32_e32 v20, 16, v57
	v_mul_f32_e32 v22, v20, v20
	v_fmac_f32_e32 v22, v21, v21
	v_mov_b32_e32 v23, v22
	s_nop 1
	v_permlane16_swap_b32_e32 v22, v23
	v_add_f32_e32 v22, v22, v23
	s_nop 1
	v_add_f32_dpp v22, v22, v22 row_ror:8 row_mask:0xf bank_mask:0xf
	s_nop 1
	v_add_f32_dpp v22, v22, v22 row_ror:4 row_mask:0xf bank_mask:0xf
	s_nop 1
	v_add_f32_dpp v22, v22, v22 quad_perm:[2,3,0,1] row_mask:0xf bank_mask:0xf
	s_nop 1
	v_add_f32_dpp v22, v22, v22 quad_perm:[1,0,3,2] row_mask:0xf bank_mask:0xf
	v_fmamk_f32 v22, v22, 0x3c800000, v170
	v_rsq_f32_e32 v22, v22
	s_nop 0
	v_mul_f32_e32 v23, v5, v22
	v_mul_f32_e32 v22, v4, v22
	v_mul_f32_e32 v22, v22, v20
	v_mul_f32_e32 v23, v23, v21
	ds_bpermute_b32 v20, v28, v22
	ds_bpermute_b32 v21, v28, v23
	s_waitcnt lgkmcnt(0)
	v_mul_f32_e32 v22, v92, v22
	v_mul_f32_e32 v23, v93, v23
	v_fmac_f32_e32 v22, v94, v20
	v_fmac_f32_e32 v23, v95, v21
	s_mov_b32 s2, 0x3e38aa3b
	v_mul_f32_e32 v20, s2, v22
	v_mul_f32_e32 v21, s2, v23
	v_cvt_pk_bf16_f32 v22, v20, v21
	v_add_co_u32_e32 v20, vcc, 0xa002000, v18
	s_nop 1
	v_addc_co_u32_e32 v21, vcc, 0, v19, vcc
	global_store_dword v[20:21], v22, off offset:768
	s_waitcnt vmcnt(29)
	v_lshlrev_b32_e32 v20, 16, v55
	v_and_b32_e32 v21, 0xffff0000, v55
	v_mul_f32_e32 v22, v20, v20
	v_fmac_f32_e32 v22, v21, v21
	v_mov_b32_e32 v23, v22
	s_nop 1
	v_permlane32_swap_b32_e32 v22, v23
	v_add_f32_e32 v22, v22, v23
	v_mov_b32_e32 v23, v22
	s_nop 1
	v_permlane16_swap_b32_e32 v22, v23
	v_add_f32_e32 v22, v22, v23
	s_nop 1
	v_add_f32_dpp v22, v22, v22 row_ror:8 row_mask:0xf bank_mask:0xf
	s_nop 1
	v_add_f32_dpp v22, v22, v22 row_ror:4 row_mask:0xf bank_mask:0xf
	s_nop 1
	v_add_f32_dpp v22, v22, v22 quad_perm:[2,3,0,1] row_mask:0xf bank_mask:0xf
	s_nop 1
	v_add_f32_dpp v22, v22, v22 quad_perm:[1,0,3,2] row_mask:0xf bank_mask:0xf
	v_fmamk_f32 v22, v22, 0x3c000000, v170
	v_rsq_f32_e32 v22, v22
	s_nop 0
	v_pk_mul_f32 v[20:21], v[22:23], v[20:21] op_sel_hi:[0,1]
	v_cvt_pk_bf16_f32 v20, v20, v21
	ds_write_b32 v59, v20 offset:272
	s_waitcnt vmcnt(28)
	v_lshlrev_b32_e32 v20, 16, v53
	v_and_b32_e32 v21, 0xffff0000, v53
	ds_bpermute_b32 v53, v28, v20
	ds_bpermute_b32 v23, v28, v21
	s_waitcnt lgkmcnt(0)
	v_mul_f32_e32 v20, v92, v20
	v_mul_f32_e32 v21, v93, v21
	v_fmac_f32_e32 v20, v94, v53
	v_fmac_f32_e32 v21, v95, v23
	v_cvt_pk_bf16_f32 v22, v20, v21
	v_add_co_u32_e32 v20, vcc, 0xa002000, v18
	s_nop 1
	v_addc_co_u32_e32 v21, vcc, 0, v19, vcc
	global_store_dword v[20:21], v22, off offset:1280
	s_waitcnt vmcnt(28)
	v_lshlrev_b32_e32 v20, 16, v52
	v_and_b32_e32 v21, 0xffff0000, v52
	ds_bpermute_b32 v52, v28, v20
	s_waitcnt lgkmcnt(1)
	ds_bpermute_b32 v23, v28, v21
	s_and_saveexec_b64 s[2:3], s[12:13]
	s_xor_b64 s[18:19], exec, s[2:3]
	s_cbranch_execz .LBB0_254
	s_and_saveexec_b64 s[30:31], s[14:15]
	s_cbranch_execz .LBB0_253
	v_mov_b32_e32 v22, v21
	s_waitcnt lgkmcnt(0)
	v_mul_f32_e32 v20, v212, v20
	v_mul_f32_e32 v21, v214, v22
	v_fmac_f32_e32 v20, v213, v52
	v_fmac_f32_e32 v21, v215, v23

; #define LAS __attribute__((address_space(3)))
; DI unsigned pk2(float lo, float hi) { f32x2 x = {lo, hi}; return __builtin_bit_cast(unsigned, __builtin_convertvector(x, bf16x2_t)); }
; DI float sum16(float v) { v += __shfl_xor(v, 8); v += __shfl_xor(v, 4); v += __shfl_xor(v, 2); v += __shfl_xor(v, 1); return v; }
; template <int HP> DI void rope2(f32x2& x, int hl, const LAS f32x2* cs) {
;   const float pa = __shfl_xor(x[0], HP), pb = __shfl_xor(x[1], HP);
;   if (hl < HP) { const f32x2 c0 = cs[2 * hl], c1 = cs[2 * hl + 1]; x[0] = x[0] * c0[0] - pa * c0[1]; x[1] = x[1] * c1[0] - pb * c1[1]; }
;   else if (hl < 2 * HP) { const f32x2 c0 = cs[2 * (hl - HP)], c1 = cs[2 * (hl - HP) + 1]; x[0] = x[0] * c0[0] + pa * c0[1]; x[1] = x[1] * c1[0] + pb * c1[1]; }
; DI void post_unit(const Params& p, int l, int unit, LAS unsigned char* lds) {
;     ...
;       } else if (s < 12) {
;         rope2<16>(x, hl, cs64 + t * 32);
;         const int hd = ((s & 1) ? 2 : 0) + hsel;
;         const float lg = log1pf(-exp2f(-5.0f - (float)hd));
;         const float f = (s < 10) ? expf(lg * (float)(t + 1)) : expf(lg * (float)(63 - t)) * 0.125f;
;         x *= f; *(unsigned*)pp = pk2(x[0], x[1]);
;       } else {
;         const float* gn = (s < 14) ? qnc : knc;
;         const float rs = rsqrtf(sum16(x[0] * x[0] + x[1] * x[1]) * (1.0f / 32.0f) + EPS);
;         x[0] *= rs * gn[2 * hl16]; x[1] *= rs * gn[2 * hl16 + 1]; rope2<2>(x, hl16, cs8 + t * 4);
;         if (s < 14) x *= LOG2E * 0.17677669529663687f;
;         *(unsigned*)pp = pk2(x[0], x[1]);
.LBB0_290:
	s_or_b64 exec, exec, s[18:19]
	v_mul_f32_e32 v22, v32, v45
	s_waitcnt lgkmcnt(0)
	v_mul_f32_e32 v23, 0x3fb8aa3b, v22
	v_fma_f32 v44, v22, s64, -v23
	v_rndne_f32_e32 v45, v23
	v_fmac_f32_e32 v44, 0x32a5705f, v22
	v_sub_f32_e32 v23, v23, v45
	v_add_f32_e32 v23, v23, v44
	v_exp_f32_e32 v23, v23
	v_cvt_i32_f32_e32 v44, v45
	v_cmp_ngt_f32_e32 vcc, s65, v22
	v_ldexp_f32 v23, v23, v44
	s_nop 0
	v_cndmask_b32_e32 v23, 0, v23, vcc
	v_cmp_nlt_f32_e32 vcc, s89, v22
	s_nop 1
	v_cndmask_b32_e32 v22, v177, v23, vcc
	v_mul_f32_e32 v22, 0x3e000000, v22
	v_pk_mul_f32 v[20:21], v[22:23], v[20:21] op_sel_hi:[0,1]
	v_cvt_pk_bf16_f32 v22, v20, v21
	v_add_co_u32_e32 v20, vcc, s77, v18
	s_nop 1
	v_addc_co_u32_e32 v21, vcc, 0, v19, vcc
	global_store_dword v[20:21], v22, off offset:3712
	s_waitcnt vmcnt(27)
	v_lshlrev_b32_e32 v20, 16, v43
	v_and_b32_e32 v21, 0xffff0000, v43
	v_mul_f32_e32 v22, v20, v20
	v_fmac_f32_e32 v22, v21, v21
	s_nop 1
	v_add_f32_dpp v22, v22, v22 row_ror:8 row_mask:0xf bank_mask:0xf
	s_nop 1
	v_add_f32_dpp v22, v22, v22 row_ror:4 row_mask:0xf bank_mask:0xf
	s_nop 1
	v_add_f32_dpp v22, v22, v22 quad_perm:[2,3,0,1] row_mask:0xf bank_mask:0xf
	s_nop 1
	v_add_f32_dpp v22, v22, v22 quad_perm:[1,0,3,2] row_mask:0xf bank_mask:0xf
	v_fmamk_f32 v22, v22, 0x3d000000, v170
	v_rsq_f32_e32 v22, v22
	s_nop 0
	v_mul_f32_e32 v23, v7, v22
	v_mul_f32_e32 v22, v6, v22
	v_mul_f32_e32 v22, v22, v20
	v_mul_f32_e32 v23, v23, v21
	ds_bpermute_b32 v20, v29, v22
	ds_bpermute_b32 v21, v29, v23
	s_and_saveexec_b64 s[2:3], s[6:7]
	s_xor_b64 s[18:19], exec, s[2:3]
	s_cbranch_execz .LBB0_294
	s_and_saveexec_b64 s[30:31], s[8:9]
	s_cbranch_execz .LBB0_293
	s_waitcnt lgkmcnt(0)
	v_pk_mul_f32 v[48:49], v[22:23], v[228:229]
	v_mul_f32_e32 v22, v229, v20
	v_mov_b32_e32 v20, v23
	v_mul_f32_e32 v20, v20, v230
	v_mul_f32_e32 v21, v21, v231
	v_mov_b32_e32 v49, v20
	v_mov_b32_e32 v23, v21
	v_pk_add_f32 v[22:23], v[48:49], v[22:23]

; #define LAS __attribute__((address_space(3)))
; DI unsigned pk2(float lo, float hi) { f32x2 x = {lo, hi}; return __builtin_bit_cast(unsigned, __builtin_convertvector(x, bf16x2_t)); }
; DI float sum16(float v) { v += __shfl_xor(v, 8); v += __shfl_xor(v, 4); v += __shfl_xor(v, 2); v += __shfl_xor(v, 1); return v; }
; template <int HP> DI void rope2(f32x2& x, int hl, const LAS f32x2* cs) {
;   const float pa = __shfl_xor(x[0], HP), pb = __shfl_xor(x[1], HP);
;   if (hl < HP) { const f32x2 c0 = cs[2 * hl], c1 = cs[2 * hl + 1]; x[0] = x[0] * c0[0] - pa * c0[1]; x[1] = x[1] * c1[0] - pb * c1[1]; }
;   else if (hl < 2 * HP) { const f32x2 c0 = cs[2 * (hl - HP)], c1 = cs[2 * (hl - HP) + 1]; x[0] = x[0] * c0[0] + pa * c0[1]; x[1] = x[1] * c1[0] + pb * c1[1]; }
; DI void post_unit(const Params& p, int l, int unit, LAS unsigned char* lds) {
;     ...
;       } else {
;         const float* gn = (s < 14) ? qnc : knc;
;         const float rs = rsqrtf(sum16(x[0] * x[0] + x[1] * x[1]) * (1.0f / 32.0f) + EPS);
;         x[0] *= rs * gn[2 * hl16]; x[1] *= rs * gn[2 * hl16 + 1]; rope2<2>(x, hl16, cs8 + t * 4);
;         if (s < 14) x *= LOG2E * 0.17677669529663687f;
;         *(unsigned*)pp = pk2(x[0], x[1]);
.LBB0_294:
	s_andn2_saveexec_b64 s[18:19], s[18:19]
	s_cbranch_execz .LBB0_296
	s_waitcnt lgkmcnt(0)
	v_pk_mul_f32 v[48:49], v[22:23], v[240:241]
	v_mul_f32_e32 v22, v241, v20
	v_mov_b32_e32 v20, v23
	v_mul_f32_e32 v20, v20, v242
	v_mul_f32_e32 v21, v21, v243
	v_mov_b32_e32 v49, v20
	v_mov_b32_e32 v23, v21
	v_pk_add_f32 v[22:23], v[48:49], v[22:23] neg_lo:[0,1] neg_hi:[0,1]
.LBB0_296:
	s_or_b64 exec, exec, s[18:19]
	s_mov_b32 s2, 0x3e8293ee
	s_waitcnt lgkmcnt(0)
	v_mul_f32_e32 v20, s2, v22
	v_mul_f32_e32 v21, s2, v23
	v_cvt_pk_bf16_f32 v22, v20, v21
	v_add_co_u32_e32 v20, vcc, 0xa003000, v18
	s_nop 1
	v_addc_co_u32_e32 v21, vcc, 0, v19, vcc
	global_store_dword v[20:21], v22, off offset:896
	s_waitcnt vmcnt(27)
	v_lshlrev_b32_e32 v20, 16, v42
	v_and_b32_e32 v21, 0xffff0000, v42
	v_mul_f32_e32 v22, v20, v20
	v_fmac_f32_e32 v22, v21, v21
	s_nop 1
	v_add_f32_dpp v22, v22, v22 row_ror:8 row_mask:0xf bank_mask:0xf
	s_nop 1
	v_add_f32_dpp v22, v22, v22 row_ror:4 row_mask:0xf bank_mask:0xf
	s_nop 1
	v_add_f32_dpp v22, v22, v22 quad_perm:[2,3,0,1] row_mask:0xf bank_mask:0xf
	s_nop 1
	v_add_f32_dpp v22, v22, v22 quad_perm:[1,0,3,2] row_mask:0xf bank_mask:0xf
	v_fmamk_f32 v22, v22, 0x3d000000, v170
	v_rsq_f32_e32 v22, v22
	s_nop 0
	v_mul_f32_e32 v23, v7, v22
	v_mul_f32_e32 v22, v6, v22
	v_mul_f32_e32 v22, v22, v20
	v_mul_f32_e32 v23, v23, v21
	ds_bpermute_b32 v20, v29, v22
	ds_bpermute_b32 v21, v29, v23
	s_waitcnt lgkmcnt(0)
	v_mul_f32_e32 v22, v96, v22
	v_mul_f32_e32 v23, v97, v23
	v_fmac_f32_e32 v22, v98, v20
	v_fmac_f32_e32 v23, v99, v21
	s_mov_b32 s2, 0x3e8293ee
	v_mul_f32_e32 v20, s2, v22
	v_mul_f32_e32 v21, s2, v23
	v_cvt_pk_bf16_f32 v22, v20, v21
	v_add_co_u32_e32 v20, vcc, 0xa003000, v18
	s_nop 1
	v_addc_co_u32_e32 v21, vcc, 0, v19, vcc
	global_store_dword v[20:21], v22, off offset:1152
	s_waitcnt vmcnt(27)
	v_lshlrev_b32_e32 v20, 16, v41
	v_and_b32_e32 v21, 0xffff0000, v41
	v_mul_f32_e32 v22, v20, v20
	v_fmac_f32_e32 v22, v21, v21
	s_nop 1
	v_add_f32_dpp v22, v22, v22 row_ror:8 row_mask:0xf bank_mask:0xf
	s_nop 1
	v_add_f32_dpp v22, v22, v22 row_ror:4 row_mask:0xf bank_mask:0xf
	s_nop 1
	v_add_f32_dpp v22, v22, v22 quad_perm:[2,3,0,1] row_mask:0xf bank_mask:0xf
	s_nop 1
	v_add_f32_dpp v22, v22, v22 quad_perm:[1,0,3,2] row_mask:0xf bank_mask:0xf
	v_fmamk_f32 v22, v22, 0x3d000000, v170
	v_rsq_f32_e32 v22, v22
	s_nop 0
	v_mul_f32_e32 v23, v9, v22
	v_mul_f32_e32 v22, v8, v22
	v_mul_f32_e32 v22, v22, v20
	v_mul_f32_e32 v23, v23, v21
	ds_bpermute_b32 v20, v29, v22
	ds_bpermute_b32 v21, v29, v23
	s_waitcnt lgkmcnt(0)
	v_mul_f32_e32 v22, v96, v22
	v_mul_f32_e32 v23, v97, v23
	v_fmac_f32_e32 v22, v98, v20
	v_fmac_f32_e32 v23, v99, v21
	s_waitcnt lgkmcnt(1)
	v_add_co_u32_e32 v20, vcc, 0xa003000, v18
	v_cvt_pk_bf16_f32 v22, v22, v23
	v_addc_co_u32_e32 v21, vcc, 0, v19, vcc
	global_store_dword v[20:21], v22, off offset:1408
	s_waitcnt vmcnt(27)
	v_lshlrev_b32_e32 v20, 16, v3
	v_and_b32_e32 v21, 0xffff0000, v3
	v_mul_f32_e32 v22, v20, v20
	v_mul_f32_e32 v23, v21, v21
	v_add_f32_e32 v3, v22, v23
	s_nop 1
	v_add_f32_dpp v3, v3, v3 row_ror:8 row_mask:0xf bank_mask:0xf
	s_nop 1
	v_add_f32_dpp v3, v3, v3 row_ror:4 row_mask:0xf bank_mask:0xf
	s_nop 1
	v_add_f32_dpp v3, v3, v3 quad_perm:[2,3,0,1] row_mask:0xf bank_mask:0xf
	s_nop 1
	v_add_f32_dpp v3, v3, v3 quad_perm:[1,0,3,2] row_mask:0xf bank_mask:0xf
	v_fmamk_f32 v3, v3, 0x3d000000, v170
	v_cmp_gt_f32_e32 vcc, s33, v3
	v_mul_f32_e32 v22, 0x4b800000, v3
	s_nop 0
	v_cndmask_b32_e32 v3, v3, v22, vcc
	v_rsq_f32_e32 v3, v3
	s_nop 0
	v_mul_f32_e32 v22, 0x45800000, v3
	v_cndmask_b32_e32 v22, v3, v22, vcc
	v_mul_f32_e32 v23, v9, v22
	v_mul_f32_e32 v22, v8, v22
	v_mul_f32_e32 v22, v22, v20
	v_mul_f32_e32 v23, v23, v21
	ds_bpermute_b32 v3, v29, v22
	ds_bpermute_b32 v21, v29, v23
	s_and_saveexec_b64 s[2:3], s[6:7]
	s_xor_b64 s[18:19], exec, s[2:3]
	s_cbranch_execz .LBB0_312
	s_and_saveexec_b64 s[30:31], s[8:9]
	s_cbranch_execz .LBB0_311
	v_mov_b32_e32 v20, v23
	s_waitcnt lgkmcnt(0)
	v_mul_f32_e32 v22, v22, v228
	v_mul_f32_e32 v23, v20, v230
	v_fmac_f32_e32 v22, v229, v3
	v_fmac_f32_e32 v23, v21, v231
